# MLA half-1 row sums deferred into the next tile's QK phase (adds moved out of the exp-heavy gaps)
# baseline (speedup 1.0000x reference)
; #define SBAR() __builtin_amdgcn_sched_barrier(0)
; template <int DVB> __device__ __forceinline__ int v_st(int k, int c) { const int kk = (k & ~0xC) | ((k & 4) << 1) | ((k & 8) >> 1); return ((kk >> 3) * DVB + (c >> 5)) * 512 + ((kk & 7) * 32 + (c & 31)) * 2; }
; __device__ __forceinline__ int v_rd_base(int lane) { return ((lane & 3) << 3) | (((lane >> 2) & 3) << 6) | (((lane >> 4) & 1) << 5) | (((lane >> 5) & 1) << 8); }
; __device__ __forceinline__ void attn_mla2(const bf16* __restrict__ Q0, const bf16* __restrict__ Q1, const bf16* __restrict__ Kn, const bf16* __restrict__ Kr, const bf16* __restrict__ Vh, ...
;     ...
;     float l0 = 0.f, l1 = 0.f;
; #pragma unroll
;     for (int rb = 0; rb < 2; ++rb)
; #pragma unroll
;         for (int d = 0; d < 2; ++d) o[rb][d] = f32x16{};
;     bf16x8 q0[6], q1[6];
; #pragma unroll
;     for (int d0 = 0; d0 < 6; ++d0) { q0[d0] = *reinterpret_cast<const bf16x8*>(Q0 + d0 * 16); q1[d0] = *reinterpret_cast<const bf16x8*>(Q1 + d0 * 16); }
;     const int kn_r = tid >> 3, kn_c = (tid & 7) * 8, kn_st = kn_r * 144 + kn_c * 2;
;     const int kr_r = (tid >> 2) & 63, kr_c = (tid & 3) * 8, kr_st = kr_r * 80 + kr_c * 2;
;     const int vst0 = v_st<2>(kn_r, kn_c);
;     const int vb0 = (int)(uintptr_t)(lds + V_OFF) + v_rd_base(lane);
;     bf16x8 s_kn, s_kr, s_v;
;     ...
;     constexpr int NT = SEQ / 64;
;     SLOAD2(0); SWRITE2(0); __syncthreads();
;     int cur = 0;
;     for (int t = 0; t < NT; ++t) {
;         const char* buf = lds + cur;
;         f32x16 pa0 = f32x16{}, pa1 = f32x16{}, pb0 = f32x16{}, pb1 = f32x16{};
;         {
;             const char* kb = buf + KN_OFF + r32 * 144 + hi * 16; const char* kr = buf + KR_OFF + r32 * 80 + hi * 16;
;     ...
;             bf16x8 c0 = KLD0(0), c1 = KLD1(0);
; #pragma unroll
;             for (int d0 = 0; d0 < 6; ++d0) {
;                 bf16x8 n0 = c0, n1 = c1;
;                 if (d0 + 1 < 6) { n0 = KLD0(d0 + 1); n1 = KLD1(d0 + 1); }
;                 pa0 = __builtin_amdgcn_mfma_f32_32x32x16_bf16(c0, q0[d0], pa0, 0, 0, 0); pb0 = __builtin_amdgcn_mfma_f32_32x32x16_bf16(c0, q1[d0], pb0, 0, 0, 0);
;                 pa1 = __builtin_amdgcn_mfma_f32_32x32x16_bf16(c1, q0[d0], pa1, 0, 0, 0); pb1 = __builtin_amdgcn_mfma_f32_32x32x16_bf16(c1, q1[d0], pb1, 0, 0, 0);
;                 SBAR(); c0 = n0; c1 = n1;
;             }
;     ...
;         }
;         if (t + 1 < NT) SLOAD2((t + 1) * 64);
.LBB0_1628:
	s_or_b64 exec, exec, s[28:29]
	v_and_or_b32 v5, v16, 8, v15
	v_lshrrev_b32_e32 v5, 2, v5
	v_lshrrev_b32_e32 v15, 5, v17
	v_or_b32_e32 v5, v5, v15
	v_and_or_b32 v13, v13, 4, v14
	v_lshlrev_b32_e32 v13, 6, v13
	v_and_b32_e32 v14, 48, v184
	v_lshl_add_u32 v5, v5, 9, 0
	s_add_i32 s17, 0, 0x3800
	v_add3_u32 v5, v5, v13, v14
	s_movk_i32 s16, 0x118
	s_cmp_lg_u32 s17, -1
	ds_write_b128 v5, v[0:3] offset:14336
	v_and_or_b32 v0, v7, s16, v12
	s_cselect_b32 s17, s17, 0
	v_and_b32_e32 v184, 0xfc0, v10
	v_add3_u32 v248, v11, s17, v0
	v_lshl_add_u64 v[0:1], s[14:15], 0, v[184:185]
	v_mov_b32_e32 v7, v185
	v_readlane_b32 s14, v255, 31
	v_lshl_add_u64 v[0:1], v[0:1], 0, v[6:7]
	v_readlane_b32 s15, v255, 32
	v_mov_b32_e32 v5, v185
	v_mov_b32_e32 v240, 0x358637bd
	v_lshl_add_u64 v[192:193], s[14:15], 0, v[0:1]
	v_and_b32_e32 v0, 0xff, v241
	v_lshlrev_b32_e32 v0, 4, v0
	v_lshlrev_b32_e32 v1, 3, v241
	v_sub_u32_e32 v0, v1, v0
	v_ashrrev_i32_e32 v1, 31, v0
	v_lshl_add_u64 v[192:193], v[192:193], 0, v[0:1]
	v_lshl_add_u64 v[0:1], s[12:13], 0, v[8:9]
	v_or_b32_e32 v0, s72, v0
	v_readlane_b32 s12, v254, 10
	v_lshl_add_u64 v[0:1], v[0:1], 0, v[4:5]
	v_readlane_b32 s14, v254, 12
	v_readlane_b32 s15, v254, 13
	s_mov_b32 s16, 0
	s_mov_b64 s[36:37], 0x20000
	v_lshl_add_u64 v[194:195], s[14:15], 0, v[0:1]
	v_mov_b32_e32 v0, 0
	s_movk_i32 s14, 0x7f
	v_mov_b32_e32 v1, v0
	v_mov_b32_e32 v2, v0
	v_mov_b32_e32 v3, v0
	v_mov_b32_e32 v4, v0
	v_mov_b32_e32 v5, v0
	v_mov_b32_e32 v6, v0
	v_mov_b32_e32 v7, v0
	v_mov_b32_e32 v8, v0
	v_mov_b32_e32 v9, v0
	v_mov_b32_e32 v10, v0
	v_mov_b32_e32 v11, v0
	v_mov_b32_e32 v12, v0
	v_mov_b32_e32 v13, v0
	v_mov_b32_e32 v14, v0
	v_mov_b32_e32 v15, v0
	v_mov_b32_e32 v16, v0
	v_mov_b32_e32 v17, v0
	v_mov_b32_e32 v18, v0
	v_mov_b32_e32 v19, v0
	v_mov_b32_e32 v20, v0
	v_mov_b32_e32 v21, v0
	v_mov_b32_e32 v22, v0
	v_mov_b32_e32 v23, v0
	v_mov_b32_e32 v24, v0
	v_mov_b32_e32 v25, v0
	v_mov_b32_e32 v26, v0
	v_mov_b32_e32 v27, v0
	v_mov_b32_e32 v28, v0
	v_mov_b32_e32 v29, v0
	v_mov_b32_e32 v30, v0
	v_mov_b32_e32 v31, v0
	v_mov_b32_e32 v32, v0
	v_mov_b32_e32 v33, v0
	v_mov_b32_e32 v34, v0
	v_mov_b32_e32 v35, v0
	v_mov_b32_e32 v36, v0
	v_mov_b32_e32 v37, v0
	v_mov_b32_e32 v38, v0
	v_mov_b32_e32 v39, v0
	v_mov_b32_e32 v40, v0
	v_mov_b32_e32 v41, v0
	v_mov_b32_e32 v42, v0
	v_mov_b32_e32 v43, v0
	v_mov_b32_e32 v44, v0
	v_mov_b32_e32 v45, v0
	v_mov_b32_e32 v46, v0
	v_mov_b32_e32 v47, v0
	v_mov_b32_e32 v48, v0
	v_mov_b32_e32 v49, v0
	v_mov_b32_e32 v50, v0
	v_mov_b32_e32 v51, v0
	v_mov_b32_e32 v52, v0
	v_mov_b32_e32 v53, v0
	v_mov_b32_e32 v54, v0
	v_mov_b32_e32 v55, v0
	v_mov_b32_e32 v56, v0
	v_mov_b32_e32 v57, v0
	v_mov_b32_e32 v58, v0
	v_mov_b32_e32 v59, v0
	v_mov_b32_e32 v60, v0
	v_mov_b32_e32 v61, v0
	v_mov_b32_e32 v62, v0
	v_mov_b32_e32 v63, v0
	v_mov_b32_e32 v190, v0
	v_mov_b32_e32 v191, v0
	s_waitcnt lgkmcnt(0)
	s_barrier
	v_readlane_b32 s13, v254, 11
	v_mov_b32_e32 v80, 0
	v_mov_b32_e32 v81, 0
	v_mov_b32_e32 v82, 0
	v_mov_b32_e32 v83, 0
	v_mov_b32_e32 v84, 0
	v_mov_b32_e32 v85, 0
	v_mov_b32_e32 v86, 0
	v_mov_b32_e32 v87, 0
	v_mov_b32_e32 v88, 0
	v_mov_b32_e32 v89, 0
	v_mov_b32_e32 v90, 0
	v_mov_b32_e32 v91, 0
	v_mov_b32_e32 v92, 0
	v_mov_b32_e32 v93, 0
	v_mov_b32_e32 v94, 0
	v_mov_b32_e32 v95, 0
	v_mov_b32_e32 v112, 0
	v_mov_b32_e32 v113, 0
	v_mov_b32_e32 v114, 0
	v_mov_b32_e32 v115, 0
	v_mov_b32_e32 v116, 0
	v_mov_b32_e32 v117, 0
	v_mov_b32_e32 v118, 0
	v_mov_b32_e32 v119, 0
	v_mov_b32_e32 v120, 0
	v_mov_b32_e32 v121, 0
	v_mov_b32_e32 v122, 0
	v_mov_b32_e32 v123, 0
	v_mov_b32_e32 v124, 0
	v_mov_b32_e32 v125, 0
	v_mov_b32_e32 v126, 0
	v_mov_b32_e32 v127, 0
.LBB0_1629:
	s_add_i32 s12, s16, 0
	v_add3_u32 v184, s12, v246, v244
	v_add3_u32 v188, s12, v245, v244
	ds_read_b128 v[196:199], v184
	ds_read_b128 v[200:203], v184 offset:32
	ds_read_b128 v[204:207], v184 offset:64
	ds_read_b128 v[208:211], v184 offset:96
	ds_read_b128 v[212:215], v188 offset:9216
	ds_read_b128 v[216:219], v188 offset:9248
	ds_read_b128 v[220:223], v184 offset:4608
	ds_read_b128 v[224:227], v184 offset:4640
	ds_read_b128 v[228:231], v184 offset:4672
	ds_read_b128 v[232:235], v184 offset:4704
	ds_read_b128 v[236:239], v188 offset:11776
	ds_read_b128 v[250:253], v188 offset:11808
	v_lshl_add_u64 v[176:177], v[194:195], 0, s[2:3]
	s_mov_b32 s12, 0x8e20000
	v_add_co_u32_e32 v178, vcc, s12, v176
	s_mov_b32 s12, 0xae20000
	s_nop 0
	v_addc_co_u32_e32 v179, vcc, 0, v177, vcc
	v_add_co_u32_e32 v176, vcc, s12, v176
	s_nop 1
	v_addc_co_u32_e32 v177, vcc, 0, v177, vcc
	global_load_dwordx4 v[180:183], v[178:179], off
	global_load_dwordx4 v[176:179], v[176:177], off
	v_lshl_add_u64 v[186:187], v[192:193], 0, s[2:3]
	global_load_dwordx2 v[186:187], v[186:187], off
	s_waitcnt lgkmcnt(11)
	v_mfma_f32_32x32x16_bf16 v[96:111], v[196:199], v[160:163], 0
	s_sub_i32 s15, 0, s16
	v_ashrrev_i32_e32 v64, 3, v241
	v_and_b32_e32 v65, 7, v241
	v_lshlrev_b32_e32 v66, 4, v65
	v_mul_u32_u24_e32 v184, 0x90, v64
	v_add_f32_e32 v190, v190, v112
	v_add_f32_e32 v191, v191, v80
	v_add_f32_e32 v190, v190, v113
	v_add_f32_e32 v191, v191, v81
	s_waitcnt lgkmcnt(10)
	v_mfma_f32_32x32x16_bf16 v[96:111], v[200:203], v[168:171], v[96:111]
	v_add3_u32 v184, s15, v184, v66
	v_mul_u32_u24_e32 v189, 0x50, v64
	v_lshlrev_b32_e32 v67, 3, v65
	v_add3_u32 v189, s15, v189, v67
	v_add_f32_e32 v190, v190, v114
	v_add_f32_e32 v191, v191, v82
	v_add_f32_e32 v190, v190, v115
	v_add_f32_e32 v191, v191, v83
	s_waitcnt lgkmcnt(9)
	v_mfma_f32_32x32x16_bf16 v[96:111], v[204:207], v[156:159], v[96:111]
	v_bfe_u32 v67, v241, 3, 2
	v_and_b32_e32 v66, 48, v66
	v_lshlrev_b32_e32 v68, 1, v64
	v_and_b32_e32 v69, 0x1fffff0, v64
	v_add_f32_e32 v190, v190, v116
	v_add_f32_e32 v191, v191, v84
	v_add_f32_e32 v190, v190, v117
	v_add_f32_e32 v191, v191, v85
	s_waitcnt lgkmcnt(8)
; #define SBAR() __builtin_amdgcn_sched_barrier(0)
; #define SLOAD2(k0) do { s_kn = *reinterpret_cast<const bf16x8*>(Kn + (size_t)((k0) + kn_r) * 1024 + kn_c); s_kr = *reinterpret_cast<const bf16x8*>(Kr + (size_t)((k0) + kr_r) * 32 + kr_c); \
;     s_v = *reinterpret_cast<const bf16x8*>(Vh + (size_t)((k0) + kn_r) * 1024 + kn_c); } while (0)
; __device__ __forceinline__ void attn_mla2(const bf16* __restrict__ Q0, const bf16* __restrict__ Q1, const bf16* __restrict__ Kn, const bf16* __restrict__ Kr, const bf16* __restrict__ Vh, ...
;     ...
;         {
;             const char* kb = buf + KN_OFF + r32 * 144 + hi * 16; const char* kr = buf + KR_OFF + r32 * 80 + hi * 16;
;     ...
;             bf16x8 c0 = KLD0(0), c1 = KLD1(0);
; #pragma unroll
;             for (int d0 = 0; d0 < 6; ++d0) {
;                 bf16x8 n0 = c0, n1 = c1;
;                 if (d0 + 1 < 6) { n0 = KLD0(d0 + 1); n1 = KLD1(d0 + 1); }
;                 pa0 = __builtin_amdgcn_mfma_f32_32x32x16_bf16(c0, q0[d0], pa0, 0, 0, 0); pb0 = __builtin_amdgcn_mfma_f32_32x32x16_bf16(c0, q1[d0], pb0, 0, 0, 0);
;                 pa1 = __builtin_amdgcn_mfma_f32_32x32x16_bf16(c1, q0[d0], pa1, 0, 0, 0); pb1 = __builtin_amdgcn_mfma_f32_32x32x16_bf16(c1, q1[d0], pb1, 0, 0, 0);
;                 SBAR(); c0 = n0; c1 = n1;
;             }
;     ...
;         }
;         if (t + 1 < NT) SLOAD2((t + 1) * 64);
;         bf16x8 fa0, fa1, fa2, fa3, fb0, fb1, fb2, fb3;
;         {   float ps = 0.f;
; #pragma unroll
;             for (int r = 0; r < 16; ++r) { pa0[r] = __builtin_amdgcn_exp2f(pa0[r]); pa1[r] = __builtin_amdgcn_exp2f(pa1[r]);     ps += pa0[r] + pa1[r]; }
;             l0 += ps; PK4(pa0, 0, fa0); PK4(pa0, 8, fa1); PK4(pa1, 0, fa2); PK4(pa1, 8, fa3); }
;         {   float ps = 0.f;
; #pragma unroll
;             for (int r = 0; r < 16; ++r) { pb0[r] = __builtin_amdgcn_exp2f(pb0[r]); pb1[r] = __builtin_amdgcn_exp2f(pb1[r]); ps += pb0[r] + pb1[r]; }
;             l1 += ps; PK4(pb0, 0, fb0); PK4(pb0, 8, fb1); PK4(pb1, 0, fb2); PK4(pb1, 8, fb3); }
	v_mfma_f32_32x32x16_bf16 v[96:111], v[208:211], v[144:147], v[96:111]
	v_and_b32_e32 v68, 8, v68
	v_or3_b32 v65, v68, v69, v65
	v_lshrrev_b32_e32 v64, 1, v64
	v_lshlrev_b32_e32 v65, 7, v65
	v_add_f32_e32 v190, v190, v118
	v_add_f32_e32 v191, v191, v86
	v_add_f32_e32 v190, v190, v119
	v_add_f32_e32 v191, v191, v87
	s_waitcnt lgkmcnt(7)
	v_mfma_f32_32x32x16_bf16 v[96:111], v[212:215], v[140:143], v[96:111]
	v_and_b32_e32 v65, 0xfffffe00, v65
	v_and_or_b32 v67, v64, 4, v67
	v_lshlrev_b32_e32 v67, 6, v67
	v_add_u32_e32 v64, s15, v65
	v_add_f32_e32 v190, v190, v120
	v_add_f32_e32 v191, v191, v88
	v_add_f32_e32 v190, v190, v121
	v_add_f32_e32 v191, v191, v89
	s_waitcnt lgkmcnt(6)
	v_mfma_f32_32x32x16_bf16 v[96:111], v[216:219], v[128:131], v[96:111]
	v_add3_u32 v188, v64, v67, v66
	v_lshl_add_u64 v[192:193], v[192:193], 0, s[30:31]
	v_lshl_add_u64 v[194:195], v[194:195], 0, s[36:37]
	s_nop 0
	v_add_f32_e32 v190, v190, v122
	v_add_f32_e32 v191, v191, v90
	v_add_f32_e32 v190, v190, v123
	v_add_f32_e32 v191, v191, v91
	v_mfma_f32_32x32x16_bf16 v[64:79], v[196:199], v[164:167], 0
	v_add_f32_e32 v190, v190, v124
	v_add_f32_e32 v191, v191, v92
	v_add_f32_e32 v190, v190, v125
	v_add_f32_e32 v191, v191, v93
	v_add_f32_e32 v190, v190, v126
	v_add_f32_e32 v191, v191, v94
	v_add_f32_e32 v190, v190, v127
	v_add_f32_e32 v191, v191, v95
	v_mfma_f32_32x32x16_bf16 v[64:79], v[200:203], v[172:175], v[64:79]
	v_exp_f32_e32 v96, v96
	v_exp_f32_e32 v97, v97
	v_add_f32_e32 v190, v190, v96
	v_exp_f32_e32 v98, v98
	v_add_f32_e32 v190, v190, v97
	v_mfma_f32_32x32x16_bf16 v[64:79], v[204:207], v[152:155], v[64:79]
	v_exp_f32_e32 v99, v99
	v_add_f32_e32 v190, v190, v98
	v_exp_f32_e32 v100, v100
	v_add_f32_e32 v190, v190, v99
	v_exp_f32_e32 v101, v101
	v_mfma_f32_32x32x16_bf16 v[64:79], v[208:211], v[148:151], v[64:79]
	v_add_f32_e32 v190, v190, v100
	v_exp_f32_e32 v102, v102
	v_add_f32_e32 v190, v190, v101
	v_exp_f32_e32 v103, v103
	v_add_f32_e32 v190, v190, v102
	v_exp_f32_e32 v104, v104
	v_mfma_f32_32x32x16_bf16 v[64:79], v[212:215], v[136:139], v[64:79]
	v_add_f32_e32 v190, v190, v103
	v_exp_f32_e32 v105, v105
	v_add_f32_e32 v190, v190, v104
	v_exp_f32_e32 v106, v106
	v_add_f32_e32 v190, v190, v105
	v_mfma_f32_32x32x16_bf16 v[64:79], v[216:219], v[132:135], v[64:79]
	v_exp_f32_e32 v107, v107
	v_add_f32_e32 v190, v190, v106
	v_exp_f32_e32 v108, v108
	v_add_f32_e32 v190, v190, v107
	v_exp_f32_e32 v109, v109
	v_and_b32_e32 v213, 32, v241
	v_mad_u32_u24 v212, v213, 24, v248
	v_add_u32_e32 v212, s16, v212
	s_waitcnt lgkmcnt(5)
	v_mfma_f32_32x32x16_bf16 v[112:127], v[220:223], v[160:163], 0
	v_add_f32_e32 v190, v190, v108
	v_exp_f32_e32 v110, v110
	v_add_f32_e32 v190, v190, v109
	v_exp_f32_e32 v111, v111
	v_add_f32_e32 v190, v190, v110
	v_add_f32_e32 v190, v190, v111
	s_waitcnt lgkmcnt(4)
	v_mfma_f32_32x32x16_bf16 v[112:127], v[224:227], v[168:171], v[112:127]
	v_exp_f32_e32 v64, v64
	v_exp_f32_e32 v65, v65
	v_add_f32_e32 v191, v191, v64
	v_exp_f32_e32 v66, v66
	v_add_f32_e32 v191, v191, v65
	s_waitcnt lgkmcnt(3)
	v_mfma_f32_32x32x16_bf16 v[112:127], v[228:231], v[156:159], v[112:127]
	v_exp_f32_e32 v67, v67
	v_add_f32_e32 v191, v191, v66
	v_exp_f32_e32 v68, v68
	v_add_f32_e32 v191, v191, v67
	v_exp_f32_e32 v69, v69
	s_waitcnt lgkmcnt(2)
	v_mfma_f32_32x32x16_bf16 v[112:127], v[232:235], v[144:147], v[112:127]
	v_add_f32_e32 v191, v191, v68
	v_exp_f32_e32 v70, v70
	v_add_f32_e32 v191, v191, v69
	v_exp_f32_e32 v71, v71
	v_add_f32_e32 v191, v191, v70
	v_exp_f32_e32 v72, v72
	s_waitcnt lgkmcnt(1)
	v_mfma_f32_32x32x16_bf16 v[112:127], v[236:239], v[140:143], v[112:127]
	v_add_f32_e32 v191, v191, v71
	v_exp_f32_e32 v73, v73
	v_add_f32_e32 v191, v191, v72
	v_exp_f32_e32 v74, v74
	v_add_f32_e32 v191, v191, v73
	s_waitcnt lgkmcnt(0)
; __device__ __forceinline__ float add_xor32(float v) { auto rr = __builtin_amdgcn_permlane32_swap(__float_as_uint(v), __float_as_uint(v), false, false); return __uint_as_float(rr[0]) + __uint_as_float(rr[1]); }
; template <int DVB> __device__ __forceinline__ int v_st(int k, int c) { const int kk = (k & ~0xC) | ((k & 4) << 1) | ((k & 8) >> 1); return ((kk >> 3) * DVB + (c >> 5)) * 512 + ((kk & 7) * 32 + (c & 31)) * 2; }
; __device__ __forceinline__ void attn_mla2(const bf16* __restrict__ Q0, const bf16* __restrict__ Q1, const bf16* __restrict__ Kn, const bf16* __restrict__ Kr, const bf16* __restrict__ Vh, ...
;     ...
;         {   float ps = 0.f;
; #pragma unroll
;             for (int r = 0; r < 16; ++r) { pa0[r] = __builtin_amdgcn_exp2f(pa0[r]); pa1[r] = __builtin_amdgcn_exp2f(pa1[r]);     ps += pa0[r] + pa1[r]; }
;             l0 += ps; PK4(pa0, 0, fa0); PK4(pa0, 8, fa1); PK4(pa1, 0, fa2); PK4(pa1, 8, fa3); }
;         {   float ps = 0.f;
; #pragma unroll
;             for (int r = 0; r < 16; ++r) { pb0[r] = __builtin_amdgcn_exp2f(pb0[r]); pb1[r] = __builtin_amdgcn_exp2f(pb1[r]); ps += pb0[r] + pb1[r]; }
;             l1 += ps; PK4(pb0, 0, fb0); PK4(pb0, 8, fb1); PK4(pb1, 0, fb2); PK4(pb1, 8, fb3); }
;         {   const int vb = vb0 + cur;
;     ...
;             PV2(0); PV2(1);
;     ...
;         }
;         if (t + 1 < NT) {
;             int tw = tid; asm volatile("" : "+v"(tw));
;             char* bb_ = lds + (BUF - cur);
;             *reinterpret_cast<bf16x8*>(bb_ + KN_OFF + (tw >> 3) * 144 + (tw & 7) * 16) = s_kn;
;             if (tw < 256) *reinterpret_cast<bf16x8*>(bb_ + KR_OFF + ((tw >> 2) & 63) * 80 + (tw & 3) * 16) = s_kr;
;             *reinterpret_cast<bf16x8*>(bb_ + V_OFF + v_st<2>(tw >> 3, (tw & 7) * 8)) = s_v;
;         }
;         __syncthreads();
;         cur = BUF - cur;
;     }
;     l0 = add_xor32(l0); l1 = add_xor32(l1);
	v_mfma_f32_32x32x16_bf16 v[112:127], v[250:253], v[128:131], v[112:127]
	v_exp_f32_e32 v75, v75
	v_add_f32_e32 v191, v191, v74
	v_exp_f32_e32 v76, v76
	v_add_f32_e32 v191, v191, v75
	v_exp_f32_e32 v77, v77
	v_mfma_f32_32x32x16_bf16 v[80:95], v[220:223], v[164:167], 0
	v_add_f32_e32 v191, v191, v76
	v_exp_f32_e32 v78, v78
	v_add_f32_e32 v191, v191, v77
	v_exp_f32_e32 v79, v79
	v_add_f32_e32 v191, v191, v78
	v_add_f32_e32 v191, v191, v79
	v_mfma_f32_32x32x16_bf16 v[80:95], v[224:227], v[172:175], v[80:95]
	v_cvt_pk_bf16_f32 v196, v96, v97
	v_cvt_pk_bf16_f32 v197, v98, v99
	v_cvt_pk_bf16_f32 v198, v100, v101
	v_cvt_pk_bf16_f32 v199, v102, v103
	v_cvt_pk_bf16_f32 v200, v104, v105
	v_cvt_pk_bf16_f32 v201, v106, v107
	v_cvt_pk_bf16_f32 v202, v108, v109
	v_cvt_pk_bf16_f32 v203, v110, v111
	v_mfma_f32_32x32x16_bf16 v[80:95], v[228:231], v[152:155], v[80:95]
	ds_read_b64_tr_b16 v[96:97], v212 offset:0
	ds_read_b64_tr_b16 v[98:99], v212 offset:256
	ds_read_b64_tr_b16 v[100:101], v212 offset:2048
	ds_read_b64_tr_b16 v[102:103], v212 offset:2304
	ds_read_b64_tr_b16 v[104:105], v212 offset:512
	ds_read_b64_tr_b16 v[106:107], v212 offset:768
	ds_read_b64_tr_b16 v[108:109], v212 offset:2560
	ds_read_b64_tr_b16 v[110:111], v212 offset:2816
	v_mfma_f32_32x32x16_bf16 v[80:95], v[232:235], v[148:151], v[80:95]
	v_cvt_pk_bf16_f32 v204, v64, v65
	v_cvt_pk_bf16_f32 v205, v66, v67
	v_cvt_pk_bf16_f32 v206, v68, v69
	v_cvt_pk_bf16_f32 v207, v70, v71
	v_cvt_pk_bf16_f32 v208, v72, v73
	v_cvt_pk_bf16_f32 v209, v74, v75
	v_cvt_pk_bf16_f32 v210, v76, v77
	v_cvt_pk_bf16_f32 v211, v78, v79
	v_mfma_f32_32x32x16_bf16 v[80:95], v[236:239], v[136:139], v[80:95]
	ds_read_b64_tr_b16 v[64:65], v212 offset:4096
	ds_read_b64_tr_b16 v[66:67], v212 offset:4352
	ds_read_b64_tr_b16 v[68:69], v212 offset:6144
	ds_read_b64_tr_b16 v[70:71], v212 offset:6400
	ds_read_b64_tr_b16 v[72:73], v212 offset:4608
	ds_read_b64_tr_b16 v[74:75], v212 offset:4864
	ds_read_b64_tr_b16 v[76:77], v212 offset:6656
	ds_read_b64_tr_b16 v[78:79], v212 offset:6912
	v_mfma_f32_32x32x16_bf16 v[80:95], v[250:253], v[132:135], v[80:95]
	v_exp_f32_e32 v112, v112
	v_exp_f32_e32 v113, v113
	v_exp_f32_e32 v114, v114
	s_waitcnt lgkmcnt(8)
	v_mfma_f32_32x32x16_bf16 v[0:15], v[196:199], v[96:99], v[0:15]
	v_exp_f32_e32 v115, v115
	v_exp_f32_e32 v116, v116
	v_exp_f32_e32 v117, v117
	v_mfma_f32_32x32x16_bf16 v[32:47], v[204:207], v[96:99], v[32:47]
	v_exp_f32_e32 v118, v118
	v_exp_f32_e32 v119, v119
	v_exp_f32_e32 v120, v120
	v_mfma_f32_32x32x16_bf16 v[16:31], v[196:199], v[104:107], v[16:31]
	v_exp_f32_e32 v121, v121
	v_exp_f32_e32 v122, v122
	v_exp_f32_e32 v123, v123
	v_mfma_f32_32x32x16_bf16 v[48:63], v[204:207], v[104:107], v[48:63]
	v_exp_f32_e32 v124, v124
	v_exp_f32_e32 v125, v125
	v_mfma_f32_32x32x16_bf16 v[0:15], v[200:203], v[100:103], v[0:15]
	v_exp_f32_e32 v126, v126
	v_exp_f32_e32 v127, v127
	s_waitcnt vmcnt(0)
	ds_write_b128 v184, v[180:183] offset:30976
	ds_write_b128 v188, v[176:179] offset:45312
	ds_write_b64 v189, v[186:187] offset:40192
	v_mfma_f32_32x32x16_bf16 v[32:47], v[208:211], v[100:103], v[32:47]
	v_cvt_pk_bf16_f32 v220, v112, v113
	v_cvt_pk_bf16_f32 v221, v114, v115
	v_cvt_pk_bf16_f32 v222, v116, v117
	v_cvt_pk_bf16_f32 v223, v118, v119
	v_cvt_pk_bf16_f32 v224, v120, v121
	v_cvt_pk_bf16_f32 v225, v122, v123
	v_cvt_pk_bf16_f32 v226, v124, v125
	v_cvt_pk_bf16_f32 v227, v126, v127
	v_mfma_f32_32x32x16_bf16 v[16:31], v[200:203], v[108:111], v[16:31]
	v_exp_f32_e32 v80, v80
	v_exp_f32_e32 v81, v81
	v_exp_f32_e32 v82, v82
	v_mfma_f32_32x32x16_bf16 v[48:63], v[208:211], v[108:111], v[48:63]
	v_exp_f32_e32 v83, v83
	v_exp_f32_e32 v84, v84
	v_exp_f32_e32 v85, v85
	s_waitcnt lgkmcnt(0)
	s_barrier
	v_mfma_f32_32x32x16_bf16 v[0:15], v[220:223], v[64:67], v[0:15]
	v_exp_f32_e32 v86, v86
	v_exp_f32_e32 v87, v87
	v_exp_f32_e32 v88, v88
	v_mfma_f32_32x32x16_bf16 v[16:31], v[220:223], v[72:75], v[16:31]
	v_exp_f32_e32 v89, v89
	v_exp_f32_e32 v90, v90
	v_exp_f32_e32 v91, v91
	v_mfma_f32_32x32x16_bf16 v[0:15], v[224:227], v[68:71], v[0:15]
	v_exp_f32_e32 v92, v92
	v_exp_f32_e32 v93, v93
	v_mfma_f32_32x32x16_bf16 v[16:31], v[224:227], v[76:79], v[16:31]
	v_exp_f32_e32 v94, v94
	v_exp_f32_e32 v95, v95
	v_cvt_pk_bf16_f32 v228, v80, v81
	v_cvt_pk_bf16_f32 v229, v82, v83
	v_cvt_pk_bf16_f32 v230, v84, v85
	v_cvt_pk_bf16_f32 v231, v86, v87
	v_cvt_pk_bf16_f32 v232, v88, v89
	v_cvt_pk_bf16_f32 v233, v90, v91
	v_cvt_pk_bf16_f32 v234, v92, v93
	v_cvt_pk_bf16_f32 v235, v94, v95
	s_sub_i32 s16, 0x7900, s16
	s_add_i32 s14, s14, -1
	s_cmp_eq_u32 s14, 0
	v_mfma_f32_32x32x16_bf16 v[32:47], v[228:231], v[64:67], v[32:47]
	v_mfma_f32_32x32x16_bf16 v[48:63], v[228:231], v[72:75], v[48:63]
	v_mfma_f32_32x32x16_bf16 v[32:47], v[232:235], v[68:71], v[32:47]
	v_mfma_f32_32x32x16_bf16 v[48:63], v[232:235], v[76:79], v[48:63]
	s_cbranch_scc1 .Lmla_flush
	v_mov_b32_e32 v240, 0x358637bd
	s_branch .LBB0_1629
.Lmla_flush:
	v_add_f32_e32 v190, v190, v112
	v_add_f32_e32 v191, v191, v80
	v_add_f32_e32 v190, v190, v113
	v_add_f32_e32 v191, v191, v81
	v_add_f32_e32 v190, v190, v114
	v_add_f32_e32 v191, v191, v82
	v_add_f32_e32 v190, v190, v115
	v_add_f32_e32 v191, v191, v83
	v_add_f32_e32 v190, v190, v116
	v_add_f32_e32 v191, v191, v84
	v_add_f32_e32 v190, v190, v117
	v_add_f32_e32 v191, v191, v85
	v_add_f32_e32 v190, v190, v118
	v_add_f32_e32 v191, v191, v86
	v_add_f32_e32 v190, v190, v119
	v_add_f32_e32 v191, v191, v87
	v_add_f32_e32 v190, v190, v120
	v_add_f32_e32 v191, v191, v88
	v_add_f32_e32 v190, v190, v121
	v_add_f32_e32 v191, v191, v89
	v_add_f32_e32 v190, v190, v122
	v_add_f32_e32 v191, v191, v90
	v_add_f32_e32 v190, v190, v123
	v_add_f32_e32 v191, v191, v91
	v_add_f32_e32 v190, v190, v124
	v_add_f32_e32 v191, v191, v92
	v_add_f32_e32 v190, v190, v125
	v_add_f32_e32 v191, v191, v93
	v_add_f32_e32 v190, v190, v126
	v_add_f32_e32 v191, v191, v94
	v_add_f32_e32 v190, v190, v127
	v_add_f32_e32 v191, v191, v95
